# fused LN epilogue: lane^16 / lane^32 stat exchanges via v_permlane16/32_swap instead of ds_bpermute (on top of clean MFMA segments)
# speedup vs baseline: 1.0089x; 1.0089x over previous
;     __device__ __forceinline__ void fused(f32x4 (&acc)[2][2][4][2], const GUnit& u, int wr, int wc, int fr, int fq, LAS unsigned char* lds, int wid, int lane) const {
;         const int rl0 = wr * 64 + fr, cl0 = wc * 32 + 8 * fq, grow0 = u.pm * 256 + rl0, gcol0 = u.pn * 256 + cl0;
;         f16* H16 = (f16*)(ws + WS_H16);
;         { u32x4 hw[2][4][2];
; #pragma unroll
;         for (int ai = 0; ai < 2; ++ai)
; #pragma unroll
;             for (int m = 0; m < 4; ++m)
; #pragma unroll
;                 for (int bj = 0; bj < 2; ++bj) hw[ai][m][bj] = *(const u32x4*)(H16 + (size_t)(grow0 + ai * 128 + m * 16) * 1024 + gcol0 + bj * 128);
;         asm volatile("" ::: "memory");
; #pragma unroll
;         for (int ai = 0; ai < 2; ++ai)
; #pragma unroll
;             for (int m = 0; m < 4; ++m) {
; #pragma unroll
;                 for (int bj = 0; bj < 2; ++bj) { f32x4 h0, h1; unpk8(hw[ai][m][bj], h0, h1);
;                     acc[ai][bj][m][0] += ALPHA * h0; acc[ai][bj][m][1] += ALPHA * h1;
;                 }
.LBB0_432:
	s_andn2_b64 vcc, exec, s[2:3]
	s_cbranch_vccnz .LBB0_567
	v_mbcnt_lo_u32_b32 v32, -1, 0
	v_mbcnt_hi_u32_b32 v32, -1, v32
	s_lshl_b32 s2, s34, 8
	v_ashrrev_i32_e32 v34, 1, v32
	v_readlane_b32 s3, v251, 28
	v_and_or_b32 v233, v32, 15, s48
	v_and_b32_e32 v34, -8, v34
	s_lshl_b32 s14, s37, 8
	s_or_b32 s2, s2, s3
	v_add_u32_e32 v214, s14, v233
	v_add_u32_e32 v198, s2, v34
	v_readlane_b32 s2, v253, 4
	v_ashrrev_i32_e32 v199, 31, v198
	v_readlane_b32 s3, v253, 5
	v_ashrrev_i32_e32 v215, 31, v214
	v_lshlrev_b64 v[216:217], 11, v[214:215]
	v_lshl_add_u64 v[136:137], v[198:199], 1, s[2:3]
	v_lshl_add_u64 v[34:35], v[136:137], 0, v[216:217]
	global_load_dwordx4 v[192:195], v[34:35], off
	global_load_dwordx4 v[188:191], v[34:35], off offset:256
	v_or_b32_e32 v34, 16, v214
	v_ashrrev_i32_e32 v35, 31, v34
	v_lshlrev_b64 v[34:35], 11, v[34:35]
	v_lshl_add_u64 v[34:35], v[136:137], 0, v[34:35]
	global_load_dwordx4 v[184:187], v[34:35], off
	global_load_dwordx4 v[180:183], v[34:35], off offset:256
	v_or_b32_e32 v34, 32, v214
	v_ashrrev_i32_e32 v35, 31, v34
	v_lshlrev_b64 v[34:35], 11, v[34:35]
	v_lshl_add_u64 v[34:35], v[136:137], 0, v[34:35]
	global_load_dwordx4 v[176:179], v[34:35], off
	global_load_dwordx4 v[172:175], v[34:35], off offset:256
	v_or_b32_e32 v34, 48, v214
	v_ashrrev_i32_e32 v35, 31, v34
	v_lshlrev_b64 v[34:35], 11, v[34:35]
	v_lshl_add_u64 v[34:35], v[136:137], 0, v[34:35]
	global_load_dwordx4 v[168:171], v[34:35], off
	global_load_dwordx4 v[164:167], v[34:35], off offset:256
	v_add_u32_e32 v212, 0x80, v214
	v_ashrrev_i32_e32 v213, 31, v212
	v_lshlrev_b64 v[210:211], 11, v[212:213]
	v_lshl_add_u64 v[34:35], v[136:137], 0, v[210:211]
	global_load_dwordx4 v[160:163], v[34:35], off
	global_load_dwordx4 v[156:159], v[34:35], off offset:256
	v_add_u32_e32 v208, 0x90, v214
	v_ashrrev_i32_e32 v209, 31, v208
	v_lshlrev_b64 v[34:35], 11, v[208:209]
	v_lshl_add_u64 v[132:133], v[136:137], 0, v[34:35]
	global_load_dwordx4 v[152:155], v[132:133], off
	global_load_dwordx4 v[144:147], v[132:133], off offset:256
	v_add_u32_e32 v206, 0xa0, v214
	v_ashrrev_i32_e32 v207, 31, v206
	v_lshlrev_b64 v[204:205], 11, v[206:207]
	v_lshl_add_u64 v[132:133], v[136:137], 0, v[204:205]
	global_load_dwordx4 v[140:143], v[132:133], off
	s_nop 0
	global_load_dwordx4 v[132:135], v[132:133], off offset:256
	v_add_u32_e32 v200, 0xb0, v214
	v_ashrrev_i32_e32 v201, 31, v200
	v_lshlrev_b64 v[202:203], 11, v[200:201]
	v_lshl_add_u64 v[136:137], v[136:137], 0, v[202:203]
	global_load_dwordx4 v[148:151], v[136:137], off
	s_nop 0
	global_load_dwordx4 v[136:139], v[136:137], off offset:256
	s_mov_b32 s2, 0x3fd744fd
	v_mov_b32_e32 v226, 0x5800
	v_cmp_gt_u32_e32 vcc, 16, v32
	s_waitcnt vmcnt(0)
	v_cvt_f32_f16_e32 v234, v192
	v_cvt_f32_f16_sdwa v235, v192 dst_sel:DWORD dst_unused:UNUSED_PAD src0_sel:WORD_1
	v_cvt_f32_f16_e32 v192, v193
	v_cvt_f32_f16_sdwa v193, v193 dst_sel:DWORD dst_unused:UNUSED_PAD src0_sel:WORD_1
	v_cvt_f32_f16_e32 v236, v194
	v_cvt_f32_f16_sdwa v237, v194 dst_sel:DWORD dst_unused:UNUSED_PAD src0_sel:WORD_1
	v_cvt_f32_f16_e32 v194, v195
	v_cvt_f32_f16_sdwa v195, v195 dst_sel:DWORD dst_unused:UNUSED_PAD src0_sel:WORD_1
	v_pk_fma_f32 v[130:131], v[192:193], s[2:3], v[130:131] op_sel_hi:[1,0,1]
	v_cvt_f32_f16_e32 v192, v188
	v_cvt_f32_f16_sdwa v193, v188 dst_sel:DWORD dst_unused:UNUSED_PAD src0_sel:WORD_1
	v_pk_fma_f32 v[126:127], v[194:195], s[2:3], v[126:127] op_sel_hi:[1,0,1]
	v_cvt_f32_f16_e32 v188, v189
	v_cvt_f32_f16_sdwa v189, v189 dst_sel:DWORD dst_unused:UNUSED_PAD src0_sel:WORD_1
	v_cvt_f32_f16_e32 v194, v190
	v_cvt_f32_f16_sdwa v195, v190 dst_sel:DWORD dst_unused:UNUSED_PAD src0_sel:WORD_1
	v_cvt_f32_f16_e32 v190, v191
	v_cvt_f32_f16_sdwa v191, v191 dst_sel:DWORD dst_unused:UNUSED_PAD src0_sel:WORD_1
	v_pk_fma_f32 v[122:123], v[188:189], s[2:3], v[122:123] op_sel_hi:[1,0,1]
	v_cvt_f32_f16_e32 v188, v184
	v_cvt_f32_f16_sdwa v189, v184 dst_sel:DWORD dst_unused:UNUSED_PAD src0_sel:WORD_1
	v_pk_fma_f32 v[118:119], v[190:191], s[2:3], v[118:119] op_sel_hi:[1,0,1]
	v_cvt_f32_f16_e32 v184, v185
	v_cvt_f32_f16_sdwa v185, v185 dst_sel:DWORD dst_unused:UNUSED_PAD src0_sel:WORD_1
	v_cvt_f32_f16_e32 v190, v186
	v_cvt_f32_f16_sdwa v191, v186 dst_sel:DWORD dst_unused:UNUSED_PAD src0_sel:WORD_1
	v_cvt_f32_f16_e32 v186, v187
	v_cvt_f32_f16_sdwa v187, v187 dst_sel:DWORD dst_unused:UNUSED_PAD src0_sel:WORD_1
	v_pk_fma_f32 v[114:115], v[184:185], s[2:3], v[114:115] op_sel_hi:[1,0,1]
	v_cvt_f32_f16_e32 v184, v180
	v_cvt_f32_f16_sdwa v185, v180 dst_sel:DWORD dst_unused:UNUSED_PAD src0_sel:WORD_1
	v_pk_fma_f32 v[110:111], v[186:187], s[2:3], v[110:111] op_sel_hi:[1,0,1]
	v_cvt_f32_f16_e32 v180, v181
	v_cvt_f32_f16_sdwa v181, v181 dst_sel:DWORD dst_unused:UNUSED_PAD src0_sel:WORD_1
	v_cvt_f32_f16_e32 v186, v182
	v_cvt_f32_f16_sdwa v187, v182 dst_sel:DWORD dst_unused:UNUSED_PAD src0_sel:WORD_1
	v_cvt_f32_f16_e32 v182, v183
	v_cvt_f32_f16_sdwa v183, v183 dst_sel:DWORD dst_unused:UNUSED_PAD src0_sel:WORD_1
	v_pk_fma_f32 v[106:107], v[180:181], s[2:3], v[106:107] op_sel_hi:[1,0,1]
	v_cvt_f32_f16_e32 v180, v176
	v_cvt_f32_f16_sdwa v181, v176 dst_sel:DWORD dst_unused:UNUSED_PAD src0_sel:WORD_1
	v_pk_fma_f32 v[102:103], v[182:183], s[2:3], v[102:103] op_sel_hi:[1,0,1]
	v_cvt_f32_f16_e32 v176, v177
	v_cvt_f32_f16_sdwa v177, v177 dst_sel:DWORD dst_unused:UNUSED_PAD src0_sel:WORD_1
	v_cvt_f32_f16_e32 v182, v178
	v_cvt_f32_f16_sdwa v183, v178 dst_sel:DWORD dst_unused:UNUSED_PAD src0_sel:WORD_1
	v_cvt_f32_f16_e32 v178, v179
	v_cvt_f32_f16_sdwa v179, v179 dst_sel:DWORD dst_unused:UNUSED_PAD src0_sel:WORD_1
	v_pk_fma_f32 v[98:99], v[176:177], s[2:3], v[98:99] op_sel_hi:[1,0,1]
;     __device__ __forceinline__ void fused(f32x4 (&acc)[2][2][4][2], const GUnit& u, int wr, int wc, int fr, int fq, LAS unsigned char* lds, int wid, int lane) const {
;     ...
;         for (int ai = 0; ai < 2; ++ai)
; #pragma unroll
;             for (int m = 0; m < 4; ++m) {
; #pragma unroll
;                 for (int bj = 0; bj < 2; ++bj) { f32x4 h0, h1; unpk8(hw[ai][m][bj], h0, h1);
;                     acc[ai][bj][m][0] += ALPHA * h0; acc[ai][bj][m][1] += ALPHA * h1;
;                 }
	v_cvt_f32_f16_e32 v176, v172
	v_cvt_f32_f16_sdwa v177, v172 dst_sel:DWORD dst_unused:UNUSED_PAD src0_sel:WORD_1
	v_pk_fma_f32 v[94:95], v[178:179], s[2:3], v[94:95] op_sel_hi:[1,0,1]
	v_cvt_f32_f16_e32 v172, v173
	v_cvt_f32_f16_sdwa v173, v173 dst_sel:DWORD dst_unused:UNUSED_PAD src0_sel:WORD_1
	v_cvt_f32_f16_e32 v178, v174
	v_cvt_f32_f16_sdwa v179, v174 dst_sel:DWORD dst_unused:UNUSED_PAD src0_sel:WORD_1
	v_cvt_f32_f16_e32 v174, v175
	v_cvt_f32_f16_sdwa v175, v175 dst_sel:DWORD dst_unused:UNUSED_PAD src0_sel:WORD_1
	v_pk_fma_f32 v[90:91], v[172:173], s[2:3], v[90:91] op_sel_hi:[1,0,1]
	v_cvt_f32_f16_e32 v172, v168
	v_cvt_f32_f16_sdwa v173, v168 dst_sel:DWORD dst_unused:UNUSED_PAD src0_sel:WORD_1
	v_pk_fma_f32 v[86:87], v[174:175], s[2:3], v[86:87] op_sel_hi:[1,0,1]
	v_cvt_f32_f16_e32 v168, v169
	v_cvt_f32_f16_sdwa v169, v169 dst_sel:DWORD dst_unused:UNUSED_PAD src0_sel:WORD_1
	v_cvt_f32_f16_e32 v174, v170
	v_cvt_f32_f16_sdwa v175, v170 dst_sel:DWORD dst_unused:UNUSED_PAD src0_sel:WORD_1
	v_cvt_f32_f16_e32 v170, v171
	v_cvt_f32_f16_sdwa v171, v171 dst_sel:DWORD dst_unused:UNUSED_PAD src0_sel:WORD_1
	v_pk_fma_f32 v[82:83], v[168:169], s[2:3], v[82:83] op_sel_hi:[1,0,1]
	v_cvt_f32_f16_e32 v168, v164
	v_cvt_f32_f16_sdwa v169, v164 dst_sel:DWORD dst_unused:UNUSED_PAD src0_sel:WORD_1
	v_pk_fma_f32 v[78:79], v[170:171], s[2:3], v[78:79] op_sel_hi:[1,0,1]
	v_cvt_f32_f16_e32 v164, v165
	v_cvt_f32_f16_sdwa v165, v165 dst_sel:DWORD dst_unused:UNUSED_PAD src0_sel:WORD_1
	v_cvt_f32_f16_e32 v170, v166
	v_cvt_f32_f16_sdwa v171, v166 dst_sel:DWORD dst_unused:UNUSED_PAD src0_sel:WORD_1
	v_cvt_f32_f16_e32 v166, v167
	v_cvt_f32_f16_sdwa v167, v167 dst_sel:DWORD dst_unused:UNUSED_PAD src0_sel:WORD_1
	v_pk_fma_f32 v[74:75], v[164:165], s[2:3], v[74:75] op_sel_hi:[1,0,1]
	v_cvt_f32_f16_e32 v164, v160
	v_cvt_f32_f16_sdwa v165, v160 dst_sel:DWORD dst_unused:UNUSED_PAD src0_sel:WORD_1
	v_pk_fma_f32 v[70:71], v[166:167], s[2:3], v[70:71] op_sel_hi:[1,0,1]
	v_cvt_f32_f16_e32 v160, v161
	v_cvt_f32_f16_sdwa v161, v161 dst_sel:DWORD dst_unused:UNUSED_PAD src0_sel:WORD_1
	v_cvt_f32_f16_e32 v166, v162
	v_cvt_f32_f16_sdwa v167, v162 dst_sel:DWORD dst_unused:UNUSED_PAD src0_sel:WORD_1
	v_cvt_f32_f16_e32 v162, v163
	v_cvt_f32_f16_sdwa v163, v163 dst_sel:DWORD dst_unused:UNUSED_PAD src0_sel:WORD_1
	v_pk_fma_f32 v[66:67], v[160:161], s[2:3], v[66:67] op_sel_hi:[1,0,1]
	v_cvt_f32_f16_e32 v160, v156
	v_cvt_f32_f16_sdwa v161, v156 dst_sel:DWORD dst_unused:UNUSED_PAD src0_sel:WORD_1
	v_pk_fma_f32 v[62:63], v[162:163], s[2:3], v[62:63] op_sel_hi:[1,0,1]
	v_cvt_f32_f16_e32 v156, v157
	v_cvt_f32_f16_sdwa v157, v157 dst_sel:DWORD dst_unused:UNUSED_PAD src0_sel:WORD_1
	v_cvt_f32_f16_e32 v162, v158
	v_cvt_f32_f16_sdwa v163, v158 dst_sel:DWORD dst_unused:UNUSED_PAD src0_sel:WORD_1
	v_cvt_f32_f16_e32 v158, v159
	v_cvt_f32_f16_sdwa v159, v159 dst_sel:DWORD dst_unused:UNUSED_PAD src0_sel:WORD_1
	v_pk_fma_f32 v[58:59], v[156:157], s[2:3], v[58:59] op_sel_hi:[1,0,1]
	v_cvt_f32_f16_e32 v156, v152
	v_cvt_f32_f16_sdwa v157, v152 dst_sel:DWORD dst_unused:UNUSED_PAD src0_sel:WORD_1
	v_pk_fma_f32 v[54:55], v[158:159], s[2:3], v[54:55] op_sel_hi:[1,0,1]
	v_cvt_f32_f16_e32 v152, v153
	v_cvt_f32_f16_sdwa v153, v153 dst_sel:DWORD dst_unused:UNUSED_PAD src0_sel:WORD_1
	v_cvt_f32_f16_e32 v158, v154
	v_cvt_f32_f16_sdwa v159, v154 dst_sel:DWORD dst_unused:UNUSED_PAD src0_sel:WORD_1
	v_cvt_f32_f16_e32 v154, v155
	v_cvt_f32_f16_sdwa v155, v155 dst_sel:DWORD dst_unused:UNUSED_PAD src0_sel:WORD_1
	v_pk_fma_f32 v[50:51], v[152:153], s[2:3], v[50:51] op_sel_hi:[1,0,1]
	v_cvt_f32_f16_e32 v152, v144
	v_cvt_f32_f16_sdwa v153, v144 dst_sel:DWORD dst_unused:UNUSED_PAD src0_sel:WORD_1
	v_pk_fma_f32 v[46:47], v[154:155], s[2:3], v[46:47] op_sel_hi:[1,0,1]
	v_cvt_f32_f16_e32 v144, v145
	v_cvt_f32_f16_sdwa v145, v145 dst_sel:DWORD dst_unused:UNUSED_PAD src0_sel:WORD_1
	v_cvt_f32_f16_e32 v154, v146
	v_cvt_f32_f16_sdwa v155, v146 dst_sel:DWORD dst_unused:UNUSED_PAD src0_sel:WORD_1
	v_cvt_f32_f16_e32 v146, v147
	v_cvt_f32_f16_sdwa v147, v147 dst_sel:DWORD dst_unused:UNUSED_PAD src0_sel:WORD_1
	v_pk_fma_f32 v[42:43], v[144:145], s[2:3], v[42:43] op_sel_hi:[1,0,1]
	v_cvt_f32_f16_e32 v144, v140
	v_cvt_f32_f16_sdwa v145, v140 dst_sel:DWORD dst_unused:UNUSED_PAD src0_sel:WORD_1
	v_pk_fma_f32 v[38:39], v[146:147], s[2:3], v[38:39] op_sel_hi:[1,0,1]
	v_cvt_f32_f16_e32 v140, v141
	v_cvt_f32_f16_sdwa v141, v141 dst_sel:DWORD dst_unused:UNUSED_PAD src0_sel:WORD_1
	v_cvt_f32_f16_e32 v146, v142
	v_cvt_f32_f16_sdwa v147, v142 dst_sel:DWORD dst_unused:UNUSED_PAD src0_sel:WORD_1
	v_cvt_f32_f16_e32 v142, v143
	v_cvt_f32_f16_sdwa v143, v143 dst_sel:DWORD dst_unused:UNUSED_PAD src0_sel:WORD_1
	v_pk_fma_f32 v[30:31], v[140:141], s[2:3], v[30:31] op_sel_hi:[1,0,1]
	v_cvt_f32_f16_e32 v140, v132
	v_cvt_f32_f16_sdwa v141, v132 dst_sel:DWORD dst_unused:UNUSED_PAD src0_sel:WORD_1
	v_pk_fma_f32 v[26:27], v[142:143], s[2:3], v[26:27] op_sel_hi:[1,0,1]
	v_cvt_f32_f16_e32 v132, v133
	v_cvt_f32_f16_sdwa v133, v133 dst_sel:DWORD dst_unused:UNUSED_PAD src0_sel:WORD_1
	v_cvt_f32_f16_e32 v142, v134
	v_cvt_f32_f16_sdwa v143, v134 dst_sel:DWORD dst_unused:UNUSED_PAD src0_sel:WORD_1
	v_cvt_f32_f16_e32 v134, v135
	v_cvt_f32_f16_sdwa v135, v135 dst_sel:DWORD dst_unused:UNUSED_PAD src0_sel:WORD_1
	v_pk_fma_f32 v[22:23], v[132:133], s[2:3], v[22:23] op_sel_hi:[1,0,1]
	v_cvt_f32_f16_e32 v132, v148
	v_cvt_f32_f16_sdwa v133, v148 dst_sel:DWORD dst_unused:UNUSED_PAD src0_sel:WORD_1
	v_pk_fma_f32 v[18:19], v[134:135], s[2:3], v[18:19] op_sel_hi:[1,0,1]
	v_cvt_f32_f16_e32 v134, v149
	v_cvt_f32_f16_sdwa v135, v149 dst_sel:DWORD dst_unused:UNUSED_PAD src0_sel:WORD_1
; #define LAS __attribute__((address_space(3)))
; __device__ __forceinline__ float shx(float v, int mask) { return __builtin_bit_cast(float, __builtin_amdgcn_ds_bpermute((lane_now() ^ mask) << 2, __builtin_bit_cast(int, v))); }
;     __device__ __forceinline__ void fused(f32x4 (&acc)[2][2][4][2], const GUnit& u, int wr, int wc, int fr, int fq, LAS unsigned char* lds, int wid, int lane) const {
;     ...
;                 for (int bj = 0; bj < 2; ++bj) { f32x4 h0, h1; unpk8(hw[ai][m][bj], h0, h1);
;                     acc[ai][bj][m][0] += ALPHA * h0; acc[ai][bj][m][1] += ALPHA * h1;
;                 }
;                 asm volatile("" : "+v"(acc[ai][0][m][0]), "+v"(acc[ai][0][m][1]), "+v"(acc[ai][1][m][0]), "+v"(acc[ai][1][m][1])); } }
;         LAS f32x2* P = (LAS f32x2*)lds; LAS f32x2* S = (LAS f32x2*)(lds + 8192); LAS unsigned* flag = (LAS unsigned*)(lds + 8192 + 2048);
;         unsigned* xbuf = (unsigned*)(ws + WS_X); unsigned* tmo = (unsigned*)(ws + WS_CTL) + CW_TMO;
; #pragma unroll
;         for (int ai = 0; ai < 2; ++ai)
; #pragma unroll
;             for (int m = 0; m < 4; ++m) {
;                 float s = 0.f;
; #pragma unroll
;                 for (int bj = 0; bj < 2; ++bj)
; #pragma unroll
;                     for (int n = 0; n < 2; ++n) { const f32x4 x = acc[ai][bj][m][n]; s += (x[0] + x[1]) + (x[2] + x[3]); }
;                 s += shx(s, 16); s += shx(s, 32);
;                 const float mw = s * (1.0f / 64.0f); float q = 0.f;
; #pragma unroll
;                 for (int bj = 0; bj < 2; ++bj)
; #pragma unroll
;                     for (int n = 0; n < 2; ++n) { const f32x4 d = acc[ai][bj][m][n] - mw; q += (d[0] * d[0] + d[1] * d[1]) + (d[2] * d[2] + d[3] * d[3]); }
;                 q += shx(q, 16); q += shx(q, 32);
;                 if (fq == 0) P[(ai * 128 + wr * 64 + m * 16 + fr) * 4 + wc] = (f32x2){mw, q};
	v_pk_fma_f32 v[12:13], v[132:133], s[2:3], v[12:13] op_sel_hi:[1,0,1]
	v_cvt_f32_f16_e32 v132, v136
	v_cvt_f32_f16_sdwa v133, v136 dst_sel:DWORD dst_unused:UNUSED_PAD src0_sel:WORD_1
	v_pk_fma_f32 v[14:15], v[134:135], s[2:3], v[14:15] op_sel_hi:[1,0,1]
	v_cvt_f32_f16_e32 v134, v137
	v_cvt_f32_f16_sdwa v135, v137 dst_sel:DWORD dst_unused:UNUSED_PAD src0_sel:WORD_1
	v_cvt_f32_f16_e32 v136, v138
	v_cvt_f32_f16_sdwa v137, v138 dst_sel:DWORD dst_unused:UNUSED_PAD src0_sel:WORD_1
	v_pk_fma_f32 v[128:129], v[234:235], s[2:3], v[128:129] op_sel_hi:[1,0,1]
	v_pk_fma_f32 v[124:125], v[236:237], s[2:3], v[124:125] op_sel_hi:[1,0,1]
	v_pk_fma_f32 v[120:121], v[192:193], s[2:3], v[120:121] op_sel_hi:[1,0,1]
	v_pk_fma_f32 v[116:117], v[194:195], s[2:3], v[116:117] op_sel_hi:[1,0,1]
	v_cvt_f32_f16_e32 v138, v139
	v_cvt_f32_f16_sdwa v139, v139 dst_sel:DWORD dst_unused:UNUSED_PAD src0_sel:WORD_1
	v_pk_fma_f32 v[6:7], v[134:135], s[2:3], v[6:7] op_sel_hi:[1,0,1]
	v_pk_fma_f32 v[4:5], v[132:133], s[2:3], v[4:5] op_sel_hi:[1,0,1]
	v_mov_b32_e32 v132, v129
	v_mov_b32_e32 v133, v130
	v_mov_b32_e32 v134, v128
	v_mov_b32_e32 v135, v131
	v_pk_fma_f32 v[0:1], v[136:137], s[2:3], v[0:1] op_sel_hi:[1,0,1]
	v_pk_add_f32 v[132:133], v[132:133], v[134:135]
	v_mov_b32_e32 v134, v125
	v_mov_b32_e32 v135, v126
	v_mov_b32_e32 v136, v124
	v_mov_b32_e32 v137, v127
	v_pk_fma_f32 v[20:21], v[140:141], s[2:3], v[20:21] op_sel_hi:[1,0,1]
	v_pk_fma_f32 v[16:17], v[142:143], s[2:3], v[16:17] op_sel_hi:[1,0,1]
	v_cvt_f32_f16_e32 v140, v150
	v_cvt_f32_f16_sdwa v141, v150 dst_sel:DWORD dst_unused:UNUSED_PAD src0_sel:WORD_1
	v_cvt_f32_f16_e32 v142, v151
	v_cvt_f32_f16_sdwa v143, v151 dst_sel:DWORD dst_unused:UNUSED_PAD src0_sel:WORD_1
	v_pk_add_f32 v[134:135], v[134:135], v[136:137]
	v_add_f32_e32 v132, v132, v133
	v_pk_add_f32 v[134:135], v[134:135], v[134:135] op_sel_hi:[0,1]
	v_pk_fma_f32 v[2:3], v[138:139], s[2:3], v[2:3] op_sel_hi:[1,0,1]
	v_add_f32_e32 v133, 0, v132
	v_add_f32_e32 v137, v120, v121
	v_add_f32_e32 v139, v122, v123
	v_mov_b32_e32 v136, v116
	v_mov_b32_e32 v138, v117
	v_mov_b32_e32 v134, v118
	v_mov_b32_e32 v132, v119
	v_pk_add_f32 v[136:137], v[136:137], v[138:139]
	v_pk_add_f32 v[132:133], v[134:135], v[132:133]
	v_pk_fma_f32 v[112:113], v[188:189], s[2:3], v[112:113] op_sel_hi:[1,0,1]
	v_pk_fma_f32 v[108:109], v[190:191], s[2:3], v[108:109] op_sel_hi:[1,0,1]
	v_pk_fma_f32 v[104:105], v[184:185], s[2:3], v[104:105] op_sel_hi:[1,0,1]
	v_pk_fma_f32 v[100:101], v[186:187], s[2:3], v[100:101] op_sel_hi:[1,0,1]
	v_pk_fma_f32 v[96:97], v[180:181], s[2:3], v[96:97] op_sel_hi:[1,0,1]
	v_pk_fma_f32 v[92:93], v[182:183], s[2:3], v[92:93] op_sel_hi:[1,0,1]
	v_pk_fma_f32 v[88:89], v[176:177], s[2:3], v[88:89] op_sel_hi:[1,0,1]
	v_pk_fma_f32 v[84:85], v[178:179], s[2:3], v[84:85] op_sel_hi:[1,0,1]
	v_pk_fma_f32 v[80:81], v[172:173], s[2:3], v[80:81] op_sel_hi:[1,0,1]
	v_pk_fma_f32 v[76:77], v[174:175], s[2:3], v[76:77] op_sel_hi:[1,0,1]
	v_pk_fma_f32 v[72:73], v[168:169], s[2:3], v[72:73] op_sel_hi:[1,0,1]
	v_pk_fma_f32 v[68:69], v[170:171], s[2:3], v[68:69] op_sel_hi:[1,0,1]
	v_pk_fma_f32 v[64:65], v[164:165], s[2:3], v[64:65] op_sel_hi:[1,0,1]
	v_pk_fma_f32 v[60:61], v[166:167], s[2:3], v[60:61] op_sel_hi:[1,0,1]
	v_pk_fma_f32 v[56:57], v[160:161], s[2:3], v[56:57] op_sel_hi:[1,0,1]
	v_pk_fma_f32 v[52:53], v[162:163], s[2:3], v[52:53] op_sel_hi:[1,0,1]
	v_pk_fma_f32 v[48:49], v[156:157], s[2:3], v[48:49] op_sel_hi:[1,0,1]
	v_pk_fma_f32 v[44:45], v[158:159], s[2:3], v[44:45] op_sel_hi:[1,0,1]
	v_pk_fma_f32 v[40:41], v[152:153], s[2:3], v[40:41] op_sel_hi:[1,0,1]
	v_pk_fma_f32 v[36:37], v[154:155], s[2:3], v[36:37] op_sel_hi:[1,0,1]
	v_pk_fma_f32 v[28:29], v[144:145], s[2:3], v[28:29] op_sel_hi:[1,0,1]
	v_pk_fma_f32 v[24:25], v[146:147], s[2:3], v[24:25] op_sel_hi:[1,0,1]
	v_pk_fma_f32 v[10:11], v[142:143], s[2:3], v[10:11] op_sel_hi:[1,0,1]
	v_pk_fma_f32 v[8:9], v[140:141], s[2:3], v[8:9] op_sel_hi:[1,0,1]
	v_pk_add_f32 v[132:133], v[136:137], v[132:133]
	s_nop 0
	v_add_f32_e32 v132, v132, v133
	v_readlane_b32 s2, v252, 13
	v_mov_b32_e32 v133, v132
	s_nop 1
	v_permlane16_swap_b32 v133, v132
	s_waitcnt lgkmcnt(0)
	v_add_f32_e32 v132, v132, v133
	v_mov_b32_e32 v133, v132
	s_nop 1
	v_permlane32_swap_b32 v133, v132
	s_waitcnt lgkmcnt(0)
	v_add_f32_e32 v133, v132, v133
	v_fmamk_f32 v134, v133, 0xbc800000, v131
	v_fmamk_f32 v136, v133, 0xbc800000, v129
	v_fmamk_f32 v132, v133, 0xbc800000, v130
	v_fmamk_f32 v135, v133, 0xbc800000, v128
	v_mul_f32_e32 v136, v136, v136
	v_mul_f32_e32 v134, v134, v134
	v_fmac_f32_e32 v136, v135, v135
	v_fmac_f32_e32 v134, v132, v132
	v_fmamk_f32 v135, v133, 0xbc800000, v127
	v_fmamk_f32 v137, v133, 0xbc800000, v125
	v_add_f32_e32 v132, v136, v134
	v_fmamk_f32 v134, v133, 0xbc800000, v126
	v_fmamk_f32 v136, v133, 0xbc800000, v124
	v_mul_f32_e32 v137, v137, v137
	v_mul_f32_e32 v135, v135, v135
	v_fmac_f32_e32 v137, v136, v136
	v_fmac_f32_e32 v135, v134, v134
	v_add_f32_e32 v134, v137, v135
	v_fmamk_f32 v135, v133, 0xbc800000, v123
	v_fmamk_f32 v137, v133, 0xbc800000, v121
	v_add_f32_e32 v132, v132, v134
	v_fmamk_f32 v134, v133, 0xbc800000, v122
	v_fmamk_f32 v136, v133, 0xbc800000, v120
	v_mul_f32_e32 v137, v137, v137
	v_mul_f32_e32 v135, v135, v135
	v_fmac_f32_e32 v137, v136, v136
	v_fmac_f32_e32 v135, v134, v134
	v_add_f32_e32 v134, v137, v135
	v_fmamk_f32 v135, v133, 0xbc800000, v119
	v_fmamk_f32 v137, v133, 0xbc800000, v117
	v_add_f32_e32 v132, v134, v132
	v_fmamk_f32 v134, v133, 0xbc800000, v118
	v_fmamk_f32 v136, v133, 0xbc800000, v116
	v_mul_f32_e32 v137, v137, v137
	v_mul_f32_e32 v135, v135, v135
	v_fmac_f32_e32 v137, v136, v136
	v_fmac_f32_e32 v135, v134, v134
	v_add_f32_e32 v134, v137, v135
	v_add_f32_e32 v132, v134, v132
	v_mov_b32_e32 v134, v132
	s_nop 1
	v_permlane16_swap_b32 v134, v132
	s_waitcnt lgkmcnt(0)
	v_add_f32_e32 v134, v132, v134
	v_mov_b32_e32 v135, v134
	s_nop 1
	v_permlane32_swap_b32 v135, v134
	v_lshl_add_u32 v132, v233, 5, s2
	s_and_saveexec_b64 s[2:3], vcc
	s_cbranch_execz .LBB0_435
	v_mul_f32_e32 v136, 0x3c800000, v133
	s_waitcnt lgkmcnt(0)
	v_add_f32_e32 v137, v134, v135
	ds_write_b64 v132, v[136:137]
; __device__ __forceinline__ float shx(float v, int mask) { return __builtin_bit_cast(float, __builtin_amdgcn_ds_bpermute((lane_now() ^ mask) << 2, __builtin_bit_cast(int, v))); }
;     __device__ __forceinline__ void fused(f32x4 (&acc)[2][2][4][2], const GUnit& u, int wr, int wc, int fr, int fq, LAS unsigned char* lds, int wid, int lane) const {
;     ...
; #pragma unroll
;         for (int ai = 0; ai < 2; ++ai)
; #pragma unroll
;             for (int m = 0; m < 4; ++m) {
;                 float s = 0.f;
; #pragma unroll
;                 for (int bj = 0; bj < 2; ++bj)
; #pragma unroll
;                     for (int n = 0; n < 2; ++n) { const f32x4 x = acc[ai][bj][m][n]; s += (x[0] + x[1]) + (x[2] + x[3]); }
;                 s += shx(s, 16); s += shx(s, 32);
;                 const float mw = s * (1.0f / 64.0f); float q = 0.f;
; #pragma unroll
;                 for (int bj = 0; bj < 2; ++bj)
; #pragma unroll
;                     for (int n = 0; n < 2; ++n) { const f32x4 d = acc[ai][bj][m][n] - mw; q += (d[0] * d[0] + d[1] * d[1]) + (d[2] * d[2] + d[3] * d[3]); }
;                 q += shx(q, 16); q += shx(q, 32);
;                 if (fq == 0) P[(ai * 128 + wr * 64 + m * 16 + fr) * 4 + wc] = (f32x2){mw, q};
;             }
.LBB0_435:
	s_or_b64 exec, exec, s[2:3]
	v_mov_b32_e32 v134, v113
	s_waitcnt lgkmcnt(0)
	v_mov_b32_e32 v135, v114
	v_mov_b32_e32 v136, v112
	v_mov_b32_e32 v137, v115
	v_pk_add_f32 v[134:135], v[134:135], v[136:137]
	v_mov_b32_e32 v136, v109
	v_mov_b32_e32 v137, v110
	v_mov_b32_e32 v138, v108
	v_mov_b32_e32 v139, v111
	v_pk_add_f32 v[136:137], v[136:137], v[138:139]
	v_add_f32_e32 v133, v134, v135
	v_pk_add_f32 v[136:137], v[136:137], v[136:137] op_sel_hi:[0,1]
	v_add_f32_e32 v135, 0, v133
	v_add_f32_e32 v139, v104, v105
	v_add_f32_e32 v141, v106, v107
	v_mov_b32_e32 v138, v100
	v_mov_b32_e32 v140, v101
	v_mov_b32_e32 v136, v102
	v_mov_b32_e32 v134, v103
	v_pk_add_f32 v[138:139], v[138:139], v[140:141]
	v_pk_add_f32 v[134:135], v[136:137], v[134:135]
	s_nop 0
	v_pk_add_f32 v[134:135], v[138:139], v[134:135]
	s_nop 0
	v_add_f32_e32 v133, v134, v135
	v_mov_b32_e32 v134, v133
	s_nop 1
	v_permlane16_swap_b32 v134, v133
	s_waitcnt lgkmcnt(0)
	v_add_f32_e32 v133, v133, v134
	v_mov_b32_e32 v134, v133
	s_nop 1
	v_permlane32_swap_b32 v134, v133
	s_waitcnt lgkmcnt(0)
	v_add_f32_e32 v133, v133, v134
	v_fmamk_f32 v135, v133, 0xbc800000, v115
	v_fmamk_f32 v137, v133, 0xbc800000, v113
	v_fmamk_f32 v134, v133, 0xbc800000, v114
	v_fmamk_f32 v136, v133, 0xbc800000, v112
	v_mul_f32_e32 v137, v137, v137
	v_mul_f32_e32 v135, v135, v135
	v_fmac_f32_e32 v137, v136, v136
	v_fmac_f32_e32 v135, v134, v134
	v_fmamk_f32 v136, v133, 0xbc800000, v111
	v_fmamk_f32 v138, v133, 0xbc800000, v109
	v_add_f32_e32 v134, v137, v135
	v_fmamk_f32 v135, v133, 0xbc800000, v110
	v_fmamk_f32 v137, v133, 0xbc800000, v108
	v_mul_f32_e32 v138, v138, v138
	v_mul_f32_e32 v136, v136, v136
	v_fmac_f32_e32 v138, v137, v137
	v_fmac_f32_e32 v136, v135, v135
	v_add_f32_e32 v135, v138, v136
	v_fmamk_f32 v136, v133, 0xbc800000, v107
	v_fmamk_f32 v138, v133, 0xbc800000, v105
	v_add_f32_e32 v134, v134, v135
	v_fmamk_f32 v135, v133, 0xbc800000, v106
	v_fmamk_f32 v137, v133, 0xbc800000, v104
	v_mul_f32_e32 v138, v138, v138
	v_mul_f32_e32 v136, v136, v136
	v_fmac_f32_e32 v138, v137, v137
	v_fmac_f32_e32 v136, v135, v135
	v_add_f32_e32 v135, v138, v136
	v_fmamk_f32 v136, v133, 0xbc800000, v103
	v_fmamk_f32 v138, v133, 0xbc800000, v101
	v_add_f32_e32 v134, v135, v134
	v_fmamk_f32 v135, v133, 0xbc800000, v102
	v_fmamk_f32 v137, v133, 0xbc800000, v100
	v_mul_f32_e32 v138, v138, v138
	v_mul_f32_e32 v136, v136, v136
	v_fmac_f32_e32 v138, v137, v137
	v_fmac_f32_e32 v136, v135, v135
	v_add_f32_e32 v135, v138, v136
	v_add_f32_e32 v134, v135, v134
	v_mov_b32_e32 v135, v134
	s_nop 1
	v_permlane16_swap_b32 v135, v134
	s_waitcnt lgkmcnt(0)
	v_add_f32_e32 v134, v134, v135
	v_mov_b32_e32 v135, v134
	s_nop 1
	v_permlane32_swap_b32 v135, v134
	s_and_saveexec_b64 s[2:3], vcc
	s_cbranch_execz .LBB0_437
	v_mul_f32_e32 v136, 0x3c800000, v133
	s_waitcnt lgkmcnt(0)
	v_add_f32_e32 v137, v134, v135
	ds_write_b64 v132, v[136:137] offset:512
.LBB0_437:
	s_or_b64 exec, exec, s[2:3]
	v_mov_b32_e32 v134, v97
	s_waitcnt lgkmcnt(0)
	v_mov_b32_e32 v135, v98
	v_mov_b32_e32 v136, v96
	v_mov_b32_e32 v137, v99
	v_pk_add_f32 v[134:135], v[134:135], v[136:137]
	v_mov_b32_e32 v136, v93
	v_mov_b32_e32 v137, v94
	v_mov_b32_e32 v138, v92
	v_mov_b32_e32 v139, v95
	v_pk_add_f32 v[136:137], v[136:137], v[138:139]
	v_add_f32_e32 v133, v134, v135
	v_pk_add_f32 v[136:137], v[136:137], v[136:137] op_sel_hi:[0,1]
	v_add_f32_e32 v135, 0, v133
	v_add_f32_e32 v139, v88, v89
	v_add_f32_e32 v141, v90, v91
	v_mov_b32_e32 v138, v84
	v_mov_b32_e32 v140, v85
	v_mov_b32_e32 v136, v86
	v_mov_b32_e32 v134, v87
	v_pk_add_f32 v[138:139], v[138:139], v[140:141]
	v_pk_add_f32 v[134:135], v[136:137], v[134:135]
	s_nop 0
	v_pk_add_f32 v[134:135], v[138:139], v[134:135]
	s_nop 0
	v_add_f32_e32 v133, v134, v135
	v_mov_b32_e32 v134, v133
	s_nop 1
	v_permlane16_swap_b32 v134, v133
	s_waitcnt lgkmcnt(0)
	v_add_f32_e32 v133, v133, v134
	v_mov_b32_e32 v134, v133
	s_nop 1
	v_permlane32_swap_b32 v134, v133
	s_waitcnt lgkmcnt(0)
	v_add_f32_e32 v133, v133, v134
	v_fmamk_f32 v135, v133, 0xbc800000, v99
	v_fmamk_f32 v137, v133, 0xbc800000, v97
	v_fmamk_f32 v134, v133, 0xbc800000, v98
	v_fmamk_f32 v136, v133, 0xbc800000, v96
	v_mul_f32_e32 v137, v137, v137
	v_mul_f32_e32 v135, v135, v135
	v_fmac_f32_e32 v137, v136, v136
	v_fmac_f32_e32 v135, v134, v134
	v_fmamk_f32 v136, v133, 0xbc800000, v95
	v_fmamk_f32 v138, v133, 0xbc800000, v93
	v_add_f32_e32 v134, v137, v135
	v_fmamk_f32 v135, v133, 0xbc800000, v94
	v_fmamk_f32 v137, v133, 0xbc800000, v92
	v_mul_f32_e32 v138, v138, v138
	v_mul_f32_e32 v136, v136, v136
	v_fmac_f32_e32 v138, v137, v137
	v_fmac_f32_e32 v136, v135, v135
	v_add_f32_e32 v135, v138, v136
	v_fmamk_f32 v136, v133, 0xbc800000, v91
	v_fmamk_f32 v138, v133, 0xbc800000, v89
	v_add_f32_e32 v134, v134, v135
	v_fmamk_f32 v135, v133, 0xbc800000, v90
	v_fmamk_f32 v137, v133, 0xbc800000, v88
	v_mul_f32_e32 v138, v138, v138
	v_mul_f32_e32 v136, v136, v136
	v_fmac_f32_e32 v138, v137, v137
	v_fmac_f32_e32 v136, v135, v135
	v_add_f32_e32 v135, v138, v136
	v_fmamk_f32 v136, v133, 0xbc800000, v87
	v_fmamk_f32 v138, v133, 0xbc800000, v85
	v_add_f32_e32 v134, v135, v134
	v_fmamk_f32 v135, v133, 0xbc800000, v86
	v_fmamk_f32 v137, v133, 0xbc800000, v84
	v_mul_f32_e32 v138, v138, v138
	v_mul_f32_e32 v136, v136, v136
	v_fmac_f32_e32 v138, v137, v137
	v_fmac_f32_e32 v136, v135, v135
	v_add_f32_e32 v135, v138, v136
	v_add_f32_e32 v134, v135, v134
	v_mov_b32_e32 v135, v134
	s_nop 1
	v_permlane16_swap_b32 v135, v134
	s_waitcnt lgkmcnt(0)
	v_add_f32_e32 v134, v134, v135
	v_mov_b32_e32 v135, v134
	s_nop 1
	v_permlane32_swap_b32 v135, v134
	s_and_saveexec_b64 s[2:3], vcc
	s_cbranch_execz .LBB0_439
	v_mul_f32_e32 v136, 0x3c800000, v133
	s_waitcnt lgkmcnt(0)
	v_add_f32_e32 v137, v134, v135
	ds_write_b64 v132, v[136:137] offset:1024
; __device__ __forceinline__ float shx(float v, int mask) { return __builtin_bit_cast(float, __builtin_amdgcn_ds_bpermute((lane_now() ^ mask) << 2, __builtin_bit_cast(int, v))); }
;     __device__ __forceinline__ void fused(f32x4 (&acc)[2][2][4][2], const GUnit& u, int wr, int wc, int fr, int fq, LAS unsigned char* lds, int wid, int lane) const {
;     ...
; #pragma unroll
;         for (int ai = 0; ai < 2; ++ai)
; #pragma unroll
;             for (int m = 0; m < 4; ++m) {
;                 float s = 0.f;
; #pragma unroll
;                 for (int bj = 0; bj < 2; ++bj)
; #pragma unroll
;                     for (int n = 0; n < 2; ++n) { const f32x4 x = acc[ai][bj][m][n]; s += (x[0] + x[1]) + (x[2] + x[3]); }
;                 s += shx(s, 16); s += shx(s, 32);
;                 const float mw = s * (1.0f / 64.0f); float q = 0.f;
; #pragma unroll
;                 for (int bj = 0; bj < 2; ++bj)
; #pragma unroll
;                     for (int n = 0; n < 2; ++n) { const f32x4 d = acc[ai][bj][m][n] - mw; q += (d[0] * d[0] + d[1] * d[1]) + (d[2] * d[2] + d[3] * d[3]); }
;                 q += shx(q, 16); q += shx(q, 32);
;                 if (fq == 0) P[(ai * 128 + wr * 64 + m * 16 + fr) * 4 + wc] = (f32x2){mw, q};
;             }
.LBB0_439:
	s_or_b64 exec, exec, s[2:3]
	v_mov_b32_e32 v134, v81
	s_waitcnt lgkmcnt(0)
	v_mov_b32_e32 v135, v82
	v_mov_b32_e32 v136, v80
	v_mov_b32_e32 v137, v83
	v_pk_add_f32 v[134:135], v[134:135], v[136:137]
	v_mov_b32_e32 v136, v77
	v_mov_b32_e32 v137, v78
	v_mov_b32_e32 v138, v76
	v_mov_b32_e32 v139, v79
	v_pk_add_f32 v[136:137], v[136:137], v[138:139]
	v_add_f32_e32 v133, v134, v135
	v_pk_add_f32 v[136:137], v[136:137], v[136:137] op_sel_hi:[0,1]
	v_add_f32_e32 v135, 0, v133
	v_add_f32_e32 v139, v72, v73
	v_add_f32_e32 v141, v74, v75
	v_mov_b32_e32 v138, v68
	v_mov_b32_e32 v140, v69
	v_mov_b32_e32 v136, v70
	v_mov_b32_e32 v134, v71
	v_pk_add_f32 v[138:139], v[138:139], v[140:141]
	v_pk_add_f32 v[134:135], v[136:137], v[134:135]
	s_nop 0
	v_pk_add_f32 v[134:135], v[138:139], v[134:135]
	s_nop 0
	v_add_f32_e32 v133, v134, v135
	v_mov_b32_e32 v134, v133
	s_nop 1
	v_permlane16_swap_b32 v134, v133
	s_waitcnt lgkmcnt(0)
	v_add_f32_e32 v133, v133, v134
	v_mov_b32_e32 v134, v133
	s_nop 1
	v_permlane32_swap_b32 v134, v133
	s_waitcnt lgkmcnt(0)
	v_add_f32_e32 v133, v133, v134
	v_fmamk_f32 v135, v133, 0xbc800000, v83
	v_fmamk_f32 v137, v133, 0xbc800000, v81
	v_fmamk_f32 v134, v133, 0xbc800000, v82
	v_fmamk_f32 v136, v133, 0xbc800000, v80
	v_mul_f32_e32 v137, v137, v137
	v_mul_f32_e32 v135, v135, v135
	v_fmac_f32_e32 v137, v136, v136
	v_fmac_f32_e32 v135, v134, v134
	v_fmamk_f32 v136, v133, 0xbc800000, v79
	v_fmamk_f32 v138, v133, 0xbc800000, v77
	v_add_f32_e32 v134, v137, v135
	v_fmamk_f32 v135, v133, 0xbc800000, v78
	v_fmamk_f32 v137, v133, 0xbc800000, v76
	v_mul_f32_e32 v138, v138, v138
	v_mul_f32_e32 v136, v136, v136
	v_fmac_f32_e32 v138, v137, v137
	v_fmac_f32_e32 v136, v135, v135
	v_add_f32_e32 v135, v138, v136
	v_fmamk_f32 v136, v133, 0xbc800000, v75
	v_fmamk_f32 v138, v133, 0xbc800000, v73
	v_add_f32_e32 v134, v134, v135
	v_fmamk_f32 v135, v133, 0xbc800000, v74
	v_fmamk_f32 v137, v133, 0xbc800000, v72
	v_mul_f32_e32 v138, v138, v138
	v_mul_f32_e32 v136, v136, v136
	v_fmac_f32_e32 v138, v137, v137
	v_fmac_f32_e32 v136, v135, v135
	v_add_f32_e32 v135, v138, v136
	v_fmamk_f32 v136, v133, 0xbc800000, v71
	v_fmamk_f32 v138, v133, 0xbc800000, v69
	v_add_f32_e32 v134, v135, v134
	v_fmamk_f32 v135, v133, 0xbc800000, v70
	v_fmamk_f32 v137, v133, 0xbc800000, v68
	v_mul_f32_e32 v138, v138, v138
	v_mul_f32_e32 v136, v136, v136
	v_fmac_f32_e32 v138, v137, v137
	v_fmac_f32_e32 v136, v135, v135
	v_add_f32_e32 v135, v138, v136
	v_add_f32_e32 v134, v135, v134
	v_mov_b32_e32 v135, v134
	s_nop 1
	v_permlane16_swap_b32 v135, v134
	s_waitcnt lgkmcnt(0)
	v_add_f32_e32 v134, v134, v135
	v_mov_b32_e32 v135, v134
	s_nop 1
	v_permlane32_swap_b32 v135, v134
	s_and_saveexec_b64 s[2:3], vcc
	s_cbranch_execz .LBB0_441
	v_mul_f32_e32 v136, 0x3c800000, v133
	s_waitcnt lgkmcnt(0)
	v_add_f32_e32 v137, v134, v135
	ds_write_b64 v132, v[136:137] offset:1536
.LBB0_441:
	s_or_b64 exec, exec, s[2:3]
	v_mov_b32_e32 v134, v65
	s_waitcnt lgkmcnt(0)
	v_mov_b32_e32 v135, v66
	v_mov_b32_e32 v136, v64
	v_mov_b32_e32 v137, v67
	v_pk_add_f32 v[134:135], v[134:135], v[136:137]
	v_mov_b32_e32 v136, v61
	v_mov_b32_e32 v137, v62
	v_mov_b32_e32 v138, v60
	v_mov_b32_e32 v139, v63
	v_pk_add_f32 v[136:137], v[136:137], v[138:139]
	v_add_f32_e32 v133, v134, v135
	v_pk_add_f32 v[136:137], v[136:137], v[136:137] op_sel_hi:[0,1]
	v_add_f32_e32 v135, 0, v133
	v_add_f32_e32 v139, v56, v57
	v_add_f32_e32 v141, v58, v59
	v_mov_b32_e32 v138, v52
	v_mov_b32_e32 v140, v53
	v_mov_b32_e32 v136, v54
	v_mov_b32_e32 v134, v55
	v_pk_add_f32 v[138:139], v[138:139], v[140:141]
	v_pk_add_f32 v[134:135], v[136:137], v[134:135]
	s_nop 0
	v_pk_add_f32 v[134:135], v[138:139], v[134:135]
	s_nop 0
	v_add_f32_e32 v133, v134, v135
	v_mov_b32_e32 v134, v133
	s_nop 1
	v_permlane16_swap_b32 v134, v133
	s_waitcnt lgkmcnt(0)
	v_add_f32_e32 v133, v133, v134
	v_mov_b32_e32 v134, v133
	s_nop 1
	v_permlane32_swap_b32 v134, v133
	s_waitcnt lgkmcnt(0)
	v_add_f32_e32 v133, v133, v134
	v_fmamk_f32 v135, v133, 0xbc800000, v67
	v_fmamk_f32 v137, v133, 0xbc800000, v65
	v_fmamk_f32 v134, v133, 0xbc800000, v66
	v_fmamk_f32 v136, v133, 0xbc800000, v64
	v_mul_f32_e32 v137, v137, v137
	v_mul_f32_e32 v135, v135, v135
	v_fmac_f32_e32 v137, v136, v136
	v_fmac_f32_e32 v135, v134, v134
	v_fmamk_f32 v136, v133, 0xbc800000, v63
	v_fmamk_f32 v138, v133, 0xbc800000, v61
	v_add_f32_e32 v134, v137, v135
	v_fmamk_f32 v135, v133, 0xbc800000, v62
	v_fmamk_f32 v137, v133, 0xbc800000, v60
	v_mul_f32_e32 v138, v138, v138
	v_mul_f32_e32 v136, v136, v136
	v_fmac_f32_e32 v138, v137, v137
	v_fmac_f32_e32 v136, v135, v135
	v_add_f32_e32 v135, v138, v136
	v_fmamk_f32 v136, v133, 0xbc800000, v59
	v_fmamk_f32 v138, v133, 0xbc800000, v57
	v_add_f32_e32 v134, v134, v135
	v_fmamk_f32 v135, v133, 0xbc800000, v58
	v_fmamk_f32 v137, v133, 0xbc800000, v56
	v_mul_f32_e32 v138, v138, v138
	v_mul_f32_e32 v136, v136, v136
	v_fmac_f32_e32 v138, v137, v137
	v_fmac_f32_e32 v136, v135, v135
	v_add_f32_e32 v135, v138, v136
	v_fmamk_f32 v136, v133, 0xbc800000, v55
	v_fmamk_f32 v138, v133, 0xbc800000, v53
	v_add_f32_e32 v134, v135, v134
	v_fmamk_f32 v135, v133, 0xbc800000, v54
	v_fmamk_f32 v137, v133, 0xbc800000, v52
	v_mul_f32_e32 v138, v138, v138
	v_mul_f32_e32 v136, v136, v136
	v_fmac_f32_e32 v138, v137, v137
	v_fmac_f32_e32 v136, v135, v135
	v_add_f32_e32 v135, v138, v136
	v_add_f32_e32 v134, v135, v134
	v_mov_b32_e32 v135, v134
	s_nop 1
	v_permlane16_swap_b32 v135, v134
	s_waitcnt lgkmcnt(0)
	v_add_f32_e32 v134, v134, v135
	v_mov_b32_e32 v135, v134
	s_nop 1
	v_permlane32_swap_b32 v135, v134
	s_and_saveexec_b64 s[2:3], vcc
	s_cbranch_execz .LBB0_443
	v_mul_f32_e32 v136, 0x3c800000, v133
	s_waitcnt lgkmcnt(0)
	v_add_f32_e32 v137, v134, v135
	ds_write_b64 v132, v[136:137] offset:4096
; __device__ __forceinline__ float shx(float v, int mask) { return __builtin_bit_cast(float, __builtin_amdgcn_ds_bpermute((lane_now() ^ mask) << 2, __builtin_bit_cast(int, v))); }
;     __device__ __forceinline__ void fused(f32x4 (&acc)[2][2][4][2], const GUnit& u, int wr, int wc, int fr, int fq, LAS unsigned char* lds, int wid, int lane) const {
;     ...
; #pragma unroll
;         for (int ai = 0; ai < 2; ++ai)
; #pragma unroll
;             for (int m = 0; m < 4; ++m) {
;                 float s = 0.f;
; #pragma unroll
;                 for (int bj = 0; bj < 2; ++bj)
; #pragma unroll
;                     for (int n = 0; n < 2; ++n) { const f32x4 x = acc[ai][bj][m][n]; s += (x[0] + x[1]) + (x[2] + x[3]); }
;                 s += shx(s, 16); s += shx(s, 32);
;                 const float mw = s * (1.0f / 64.0f); float q = 0.f;
; #pragma unroll
;                 for (int bj = 0; bj < 2; ++bj)
; #pragma unroll
;                     for (int n = 0; n < 2; ++n) { const f32x4 d = acc[ai][bj][m][n] - mw; q += (d[0] * d[0] + d[1] * d[1]) + (d[2] * d[2] + d[3] * d[3]); }
;                 q += shx(q, 16); q += shx(q, 32);
;                 if (fq == 0) P[(ai * 128 + wr * 64 + m * 16 + fr) * 4 + wc] = (f32x2){mw, q};
;             }
.LBB0_443:
	s_or_b64 exec, exec, s[2:3]
	v_mov_b32_e32 v134, v49
	s_waitcnt lgkmcnt(0)
	v_mov_b32_e32 v135, v50
	v_mov_b32_e32 v136, v48
	v_mov_b32_e32 v137, v51
	v_pk_add_f32 v[134:135], v[134:135], v[136:137]
	v_mov_b32_e32 v136, v45
	v_mov_b32_e32 v137, v46
	v_mov_b32_e32 v138, v44
	v_mov_b32_e32 v139, v47
	v_pk_add_f32 v[136:137], v[136:137], v[138:139]
	v_add_f32_e32 v133, v134, v135
	v_pk_add_f32 v[136:137], v[136:137], v[136:137] op_sel_hi:[0,1]
	v_add_f32_e32 v135, 0, v133
	v_add_f32_e32 v139, v40, v41
	v_add_f32_e32 v141, v42, v43
	v_mov_b32_e32 v138, v36
	v_mov_b32_e32 v140, v37
	v_mov_b32_e32 v136, v38
	v_mov_b32_e32 v134, v39
	v_pk_add_f32 v[138:139], v[138:139], v[140:141]
	v_pk_add_f32 v[134:135], v[136:137], v[134:135]
	s_nop 0
	v_pk_add_f32 v[134:135], v[138:139], v[134:135]
	s_nop 0
	v_add_f32_e32 v133, v134, v135
	v_mov_b32_e32 v134, v133
	s_nop 1
	v_permlane16_swap_b32 v134, v133
	s_waitcnt lgkmcnt(0)
	v_add_f32_e32 v133, v133, v134
	v_mov_b32_e32 v134, v133
	s_nop 1
	v_permlane32_swap_b32 v134, v133
	s_waitcnt lgkmcnt(0)
	v_add_f32_e32 v133, v133, v134
	v_fmamk_f32 v135, v133, 0xbc800000, v51
	v_fmamk_f32 v137, v133, 0xbc800000, v49
	v_fmamk_f32 v134, v133, 0xbc800000, v50
	v_fmamk_f32 v136, v133, 0xbc800000, v48
	v_mul_f32_e32 v137, v137, v137
	v_mul_f32_e32 v135, v135, v135
	v_fmac_f32_e32 v137, v136, v136
	v_fmac_f32_e32 v135, v134, v134
	v_fmamk_f32 v136, v133, 0xbc800000, v47
	v_fmamk_f32 v138, v133, 0xbc800000, v45
	v_add_f32_e32 v134, v137, v135
	v_fmamk_f32 v135, v133, 0xbc800000, v46
	v_fmamk_f32 v137, v133, 0xbc800000, v44
	v_mul_f32_e32 v138, v138, v138
	v_mul_f32_e32 v136, v136, v136
	v_fmac_f32_e32 v138, v137, v137
	v_fmac_f32_e32 v136, v135, v135
	v_add_f32_e32 v135, v138, v136
	v_fmamk_f32 v136, v133, 0xbc800000, v43
	v_fmamk_f32 v138, v133, 0xbc800000, v41
	v_add_f32_e32 v134, v134, v135
	v_fmamk_f32 v135, v133, 0xbc800000, v42
	v_fmamk_f32 v137, v133, 0xbc800000, v40
	v_mul_f32_e32 v138, v138, v138
	v_mul_f32_e32 v136, v136, v136
	v_fmac_f32_e32 v138, v137, v137
	v_fmac_f32_e32 v136, v135, v135
	v_add_f32_e32 v135, v138, v136
	v_fmamk_f32 v136, v133, 0xbc800000, v39
	v_fmamk_f32 v138, v133, 0xbc800000, v37
	v_add_f32_e32 v134, v135, v134
	v_fmamk_f32 v135, v133, 0xbc800000, v38
	v_fmamk_f32 v137, v133, 0xbc800000, v36
	v_mul_f32_e32 v138, v138, v138
	v_mul_f32_e32 v136, v136, v136
	v_fmac_f32_e32 v138, v137, v137
	v_fmac_f32_e32 v136, v135, v135
	v_add_f32_e32 v135, v138, v136
	v_add_f32_e32 v134, v135, v134
	v_mov_b32_e32 v135, v134
	s_nop 1
	v_permlane16_swap_b32 v135, v134
	s_waitcnt lgkmcnt(0)
	v_add_f32_e32 v134, v134, v135
	v_mov_b32_e32 v135, v134
	s_nop 1
	v_permlane32_swap_b32 v135, v134
	s_and_saveexec_b64 s[2:3], vcc
	s_cbranch_execz .LBB0_445
	v_mul_f32_e32 v136, 0x3c800000, v133
	s_waitcnt lgkmcnt(0)
	v_add_f32_e32 v137, v134, v135
	ds_write_b64 v132, v[136:137] offset:4608
; __device__ __forceinline__ float shx(float v, int mask) { return __builtin_bit_cast(float, __builtin_amdgcn_ds_bpermute((lane_now() ^ mask) << 2, __builtin_bit_cast(int, v))); }
;     __device__ __forceinline__ void fused(f32x4 (&acc)[2][2][4][2], const GUnit& u, int wr, int wc, int fr, int fq, LAS unsigned char* lds, int wid, int lane) const {
;     ...
; #pragma unroll
;         for (int ai = 0; ai < 2; ++ai)
; #pragma unroll
;             for (int m = 0; m < 4; ++m) {
;                 float s = 0.f;
; #pragma unroll
;                 for (int bj = 0; bj < 2; ++bj)
; #pragma unroll
;                     for (int n = 0; n < 2; ++n) { const f32x4 x = acc[ai][bj][m][n]; s += (x[0] + x[1]) + (x[2] + x[3]); }
;                 s += shx(s, 16); s += shx(s, 32);
;                 const float mw = s * (1.0f / 64.0f); float q = 0.f;
; #pragma unroll
;                 for (int bj = 0; bj < 2; ++bj)
; #pragma unroll
;                     for (int n = 0; n < 2; ++n) { const f32x4 d = acc[ai][bj][m][n] - mw; q += (d[0] * d[0] + d[1] * d[1]) + (d[2] * d[2] + d[3] * d[3]); }
;                 q += shx(q, 16); q += shx(q, 32);
;                 if (fq == 0) P[(ai * 128 + wr * 64 + m * 16 + fr) * 4 + wc] = (f32x2){mw, q};
;             }
.LBB0_445:
	s_or_b64 exec, exec, s[2:3]
	v_mov_b32_e32 v134, v29
	s_waitcnt lgkmcnt(0)
	v_mov_b32_e32 v135, v30
	v_mov_b32_e32 v136, v28
	v_mov_b32_e32 v137, v31
	v_pk_add_f32 v[134:135], v[134:135], v[136:137]
	v_mov_b32_e32 v136, v25
	v_mov_b32_e32 v137, v26
	v_mov_b32_e32 v138, v24
	v_mov_b32_e32 v139, v27
	v_pk_add_f32 v[136:137], v[136:137], v[138:139]
	v_add_f32_e32 v133, v134, v135
	v_pk_add_f32 v[136:137], v[136:137], v[136:137] op_sel_hi:[0,1]
	v_add_f32_e32 v135, 0, v133
	v_add_f32_e32 v139, v20, v21
	v_add_f32_e32 v141, v22, v23
	v_mov_b32_e32 v138, v16
	v_mov_b32_e32 v140, v17
	v_mov_b32_e32 v136, v18
	v_mov_b32_e32 v134, v19
	v_pk_add_f32 v[138:139], v[138:139], v[140:141]
	v_pk_add_f32 v[134:135], v[136:137], v[134:135]
	s_nop 0
	v_pk_add_f32 v[134:135], v[138:139], v[134:135]
	s_nop 0
	v_add_f32_e32 v133, v134, v135
	v_mov_b32_e32 v134, v133
	s_nop 1
	v_permlane16_swap_b32 v134, v133
	s_waitcnt lgkmcnt(0)
	v_add_f32_e32 v133, v133, v134
	v_mov_b32_e32 v134, v133
	s_nop 1
	v_permlane32_swap_b32 v134, v133
	s_waitcnt lgkmcnt(0)
	v_add_f32_e32 v133, v133, v134
	v_fmamk_f32 v135, v133, 0xbc800000, v31
	v_fmamk_f32 v137, v133, 0xbc800000, v29
	v_fmamk_f32 v134, v133, 0xbc800000, v30
	v_fmamk_f32 v136, v133, 0xbc800000, v28
	v_mul_f32_e32 v137, v137, v137
	v_mul_f32_e32 v135, v135, v135
	v_fmac_f32_e32 v137, v136, v136
	v_fmac_f32_e32 v135, v134, v134
	v_fmamk_f32 v136, v133, 0xbc800000, v27
	v_fmamk_f32 v138, v133, 0xbc800000, v25
	v_add_f32_e32 v134, v137, v135
	v_fmamk_f32 v135, v133, 0xbc800000, v26
	v_fmamk_f32 v137, v133, 0xbc800000, v24
	v_mul_f32_e32 v138, v138, v138
	v_mul_f32_e32 v136, v136, v136
	v_fmac_f32_e32 v138, v137, v137
	v_fmac_f32_e32 v136, v135, v135
	v_add_f32_e32 v135, v138, v136
	v_fmamk_f32 v136, v133, 0xbc800000, v23
	v_fmamk_f32 v138, v133, 0xbc800000, v21
	v_add_f32_e32 v134, v134, v135
	v_fmamk_f32 v135, v133, 0xbc800000, v22
	v_fmamk_f32 v137, v133, 0xbc800000, v20
	v_mul_f32_e32 v138, v138, v138
	v_mul_f32_e32 v136, v136, v136
	v_fmac_f32_e32 v138, v137, v137
	v_fmac_f32_e32 v136, v135, v135
	v_add_f32_e32 v135, v138, v136
	v_fmamk_f32 v136, v133, 0xbc800000, v19
	v_fmamk_f32 v138, v133, 0xbc800000, v17
	v_add_f32_e32 v134, v135, v134
	v_fmamk_f32 v135, v133, 0xbc800000, v18
	v_fmamk_f32 v137, v133, 0xbc800000, v16
	v_mul_f32_e32 v138, v138, v138
	v_mul_f32_e32 v136, v136, v136
	v_fmac_f32_e32 v138, v137, v137
	v_fmac_f32_e32 v136, v135, v135
	v_add_f32_e32 v135, v138, v136
	v_add_f32_e32 v134, v135, v134
	v_mov_b32_e32 v135, v134
	s_nop 1
	v_permlane16_swap_b32 v135, v134
	s_waitcnt lgkmcnt(0)
	v_add_f32_e32 v134, v134, v135
	v_mov_b32_e32 v135, v134
	s_nop 1
	v_permlane32_swap_b32 v135, v134
	s_and_saveexec_b64 s[2:3], vcc
	s_cbranch_execz .LBB0_447
	v_mul_f32_e32 v136, 0x3c800000, v133
	s_waitcnt lgkmcnt(0)
	v_add_f32_e32 v137, v134, v135
	ds_write_b64 v132, v[136:137] offset:5120
.LBB0_447:
	s_or_b64 exec, exec, s[2:3]
	v_mov_b32_e32 v134, v13
	s_waitcnt lgkmcnt(0)
	v_mov_b32_e32 v135, v14
	v_mov_b32_e32 v136, v12
	v_mov_b32_e32 v137, v15
	v_pk_add_f32 v[134:135], v[134:135], v[136:137]
	v_mov_b32_e32 v136, v9
	v_mov_b32_e32 v137, v10
	v_mov_b32_e32 v138, v8
	v_mov_b32_e32 v139, v11
	v_pk_add_f32 v[136:137], v[136:137], v[138:139]
	v_add_f32_e32 v133, v134, v135
	v_pk_add_f32 v[136:137], v[136:137], v[136:137] op_sel_hi:[0,1]
	v_add_f32_e32 v135, 0, v133
	v_add_f32_e32 v139, v4, v5
	v_add_f32_e32 v141, v6, v7
	v_mov_b32_e32 v138, v0
	v_mov_b32_e32 v140, v1
	v_mov_b32_e32 v136, v2
	v_mov_b32_e32 v134, v3
	v_pk_add_f32 v[138:139], v[138:139], v[140:141]
	v_pk_add_f32 v[134:135], v[136:137], v[134:135]
	s_nop 0
	v_pk_add_f32 v[134:135], v[138:139], v[134:135]
	s_nop 0
	v_add_f32_e32 v133, v134, v135
	v_mov_b32_e32 v134, v133
	s_nop 1
	v_permlane16_swap_b32 v134, v133
	s_waitcnt lgkmcnt(0)
	v_add_f32_e32 v133, v133, v134
	v_mov_b32_e32 v134, v133
	s_nop 1
	v_permlane32_swap_b32 v134, v133
	s_waitcnt lgkmcnt(0)
	v_add_f32_e32 v133, v133, v134
	v_fmamk_f32 v135, v133, 0xbc800000, v15
	v_fmamk_f32 v137, v133, 0xbc800000, v13
	v_fmamk_f32 v134, v133, 0xbc800000, v14
	v_fmamk_f32 v136, v133, 0xbc800000, v12
	v_mul_f32_e32 v137, v137, v137
	v_mul_f32_e32 v135, v135, v135
	v_fmac_f32_e32 v137, v136, v136
	v_fmac_f32_e32 v135, v134, v134
	v_fmamk_f32 v136, v133, 0xbc800000, v11
	v_fmamk_f32 v138, v133, 0xbc800000, v9
	v_add_f32_e32 v134, v137, v135
	v_fmamk_f32 v135, v133, 0xbc800000, v10
	v_fmamk_f32 v137, v133, 0xbc800000, v8
	v_mul_f32_e32 v138, v138, v138
	v_mul_f32_e32 v136, v136, v136
	v_fmac_f32_e32 v138, v137, v137
	v_fmac_f32_e32 v136, v135, v135
	v_add_f32_e32 v135, v138, v136
	v_fmamk_f32 v136, v133, 0xbc800000, v7
	v_fmamk_f32 v138, v133, 0xbc800000, v5
	v_add_f32_e32 v134, v134, v135
	v_fmamk_f32 v135, v133, 0xbc800000, v6
	v_fmamk_f32 v137, v133, 0xbc800000, v4
	v_mul_f32_e32 v138, v138, v138
	v_mul_f32_e32 v136, v136, v136
	v_fmac_f32_e32 v138, v137, v137
	v_fmac_f32_e32 v136, v135, v135
	v_add_f32_e32 v135, v138, v136
	v_fmamk_f32 v136, v133, 0xbc800000, v3
	v_fmamk_f32 v138, v133, 0xbc800000, v1
	v_add_f32_e32 v134, v135, v134
	v_fmamk_f32 v135, v133, 0xbc800000, v2
	v_fmamk_f32 v137, v133, 0xbc800000, v0
	v_mul_f32_e32 v138, v138, v138
	v_mul_f32_e32 v136, v136, v136
	v_fmac_f32_e32 v138, v137, v137
	v_fmac_f32_e32 v136, v135, v135
	v_add_f32_e32 v135, v138, v136
	v_add_f32_e32 v134, v135, v134
	v_mov_b32_e32 v135, v134
	s_nop 1
	v_permlane16_swap_b32 v135, v134
	s_waitcnt lgkmcnt(0)
	v_add_f32_e32 v134, v134, v135
	v_mov_b32_e32 v135, v134
	s_nop 1
	v_permlane32_swap_b32 v135, v134
	s_and_saveexec_b64 s[2:3], vcc
	s_cbranch_execz .LBB0_449
	v_mul_f32_e32 v136, 0x3c800000, v133
	s_waitcnt lgkmcnt(0)
	v_add_f32_e32 v137, v134, v135
	ds_write_b64 v132, v[136:137] offset:5632
